# P4 sample-row q norm+rope: all 8 heads of a row batched (17 loads in flight, DPP/permlane reductions) instead of 8 serialized head iterations
# speedup vs baseline: 1.0016x; 1.0016x over previous
.LBB0_709:
	v_mad_i64_i32 v[6:7], s[4:5], s2, v25, v[2:3]
	v_mad_i64_i32 v[8:9], s[4:5], s2, v25, v[4:5]
	s_ashr_i32 s4, s2, 31
	s_lshr_b32 s4, s4, 21
	s_add_i32 s4, s2, s4
	s_and_b32 s4, s4, 0x7fff800
	s_sub_i32 s4, s2, s4
	s_cmp_lt_i32 s2, 0x8000
	s_cselect_b32 s4, s4, s10
	v_lshl_or_b32 v10, s4, 5, v24
	v_readlane_b32 s12, v253, 3
	v_ashrrev_i32_e32 v11, 31, v10
	v_readlane_b32 s16, v253, 7
	v_readlane_b32 s17, v253, 8
	s_mov_b64 s[4:5], 0x80
	v_readlane_b32 s13, v253, 4
	v_lshl_add_u64 v[10:11], v[10:11], 2, s[16:17]
	v_readlane_b32 s14, v253, 5
	v_readlane_b32 s15, v253, 6
	v_readlane_b32 s18, v253, 9
	v_readlane_b32 s19, v253, 10
	v_readlane_b32 s20, v253, 11
	v_readlane_b32 s21, v253, 12
	v_readlane_b32 s22, v253, 13
	v_readlane_b32 s23, v253, 14
	v_readlane_b32 s24, v253, 15
	v_readlane_b32 s25, v253, 16
	v_readlane_b32 s26, v253, 17
	v_readlane_b32 s27, v253, 18
	v_mov_b32_e32 v38, 0
	v_mov_b32_e32 v39, 0
	v_mov_b32_e32 v40, 0
	v_mov_b32_e32 v41, 0
	v_mov_b32_e32 v42, 0
	v_mov_b32_e32 v43, 0
	v_mov_b32_e32 v44, 0
	v_mov_b32_e32 v45, 0
	global_load_ushort v30, v[6:7], off
	global_load_ushort v31, v[6:7], off offset:192
	global_load_ushort v32, v[6:7], off offset:384
	global_load_ushort v33, v[6:7], off offset:576
	global_load_ushort v34, v[6:7], off offset:768
	global_load_ushort v35, v[6:7], off offset:960
	global_load_ushort v36, v[6:7], off offset:1152
	global_load_ushort v37, v[6:7], off offset:1344
	s_and_saveexec_b64 s[8:9], vcc
	global_load_ushort v38, v[6:7], off offset:128
	global_load_ushort v39, v[6:7], off offset:320
	global_load_ushort v40, v[6:7], off offset:512
	global_load_ushort v41, v[6:7], off offset:704
	global_load_ushort v42, v[6:7], off offset:896
	global_load_ushort v43, v[6:7], off offset:1088
	global_load_ushort v44, v[6:7], off offset:1280
	global_load_ushort v45, v[6:7], off offset:1472
	global_load_dwordx2 v[46:47], v[10:11], off
	s_or_b64 exec, exec, s[8:9]
	s_waitcnt vmcnt(0)
	v_lshlrev_b32_e32 v30, 16, v30
	v_lshlrev_b32_e32 v31, 16, v31
	v_lshlrev_b32_e32 v32, 16, v32
	v_lshlrev_b32_e32 v33, 16, v33
	v_lshlrev_b32_e32 v34, 16, v34
	v_lshlrev_b32_e32 v35, 16, v35
	v_lshlrev_b32_e32 v36, 16, v36
	v_lshlrev_b32_e32 v37, 16, v37
	v_lshlrev_b32_e32 v38, 16, v38
	v_lshlrev_b32_e32 v39, 16, v39
	v_lshlrev_b32_e32 v40, 16, v40
	v_lshlrev_b32_e32 v41, 16, v41
	v_lshlrev_b32_e32 v42, 16, v42
	v_lshlrev_b32_e32 v43, 16, v43
	v_lshlrev_b32_e32 v44, 16, v44
	v_lshlrev_b32_e32 v45, 16, v45
	v_mul_f32_e32 v48, v30, v30
	v_mul_f32_e32 v49, v31, v31
	v_mul_f32_e32 v50, v32, v32
	v_mul_f32_e32 v51, v33, v33
	v_mul_f32_e32 v52, v34, v34
	v_mul_f32_e32 v53, v35, v35
	v_mul_f32_e32 v54, v36, v36
	v_mul_f32_e32 v55, v37, v37
	v_mul_f32_e32 v56, v38, v38
	v_mul_f32_e32 v57, v39, v39
	v_mul_f32_e32 v58, v40, v40
	v_mul_f32_e32 v59, v41, v41
	v_mul_f32_e32 v60, v42, v42
	v_mul_f32_e32 v61, v43, v43
	v_mul_f32_e32 v62, v44, v44
	v_mul_f32_e32 v63, v45, v45
	v_add_f32_dpp v48, v48, v48 quad_perm:[1,0,3,2] row_mask:0xf bank_mask:0xf
	v_add_f32_dpp v49, v49, v49 quad_perm:[1,0,3,2] row_mask:0xf bank_mask:0xf
	v_add_f32_dpp v50, v50, v50 quad_perm:[1,0,3,2] row_mask:0xf bank_mask:0xf
	v_add_f32_dpp v51, v51, v51 quad_perm:[1,0,3,2] row_mask:0xf bank_mask:0xf
	v_add_f32_dpp v52, v52, v52 quad_perm:[1,0,3,2] row_mask:0xf bank_mask:0xf
	v_add_f32_dpp v53, v53, v53 quad_perm:[1,0,3,2] row_mask:0xf bank_mask:0xf
	v_add_f32_dpp v54, v54, v54 quad_perm:[1,0,3,2] row_mask:0xf bank_mask:0xf
	v_add_f32_dpp v55, v55, v55 quad_perm:[1,0,3,2] row_mask:0xf bank_mask:0xf
	v_add_f32_dpp v56, v56, v56 quad_perm:[1,0,3,2] row_mask:0xf bank_mask:0xf
	v_add_f32_dpp v57, v57, v57 quad_perm:[1,0,3,2] row_mask:0xf bank_mask:0xf
	v_add_f32_dpp v58, v58, v58 quad_perm:[1,0,3,2] row_mask:0xf bank_mask:0xf
	v_add_f32_dpp v59, v59, v59 quad_perm:[1,0,3,2] row_mask:0xf bank_mask:0xf
	v_add_f32_dpp v60, v60, v60 quad_perm:[1,0,3,2] row_mask:0xf bank_mask:0xf
	v_add_f32_dpp v61, v61, v61 quad_perm:[1,0,3,2] row_mask:0xf bank_mask:0xf
	v_add_f32_dpp v62, v62, v62 quad_perm:[1,0,3,2] row_mask:0xf bank_mask:0xf
	v_add_f32_dpp v63, v63, v63 quad_perm:[1,0,3,2] row_mask:0xf bank_mask:0xf
	v_add_f32_dpp v48, v48, v48 quad_perm:[2,3,0,1] row_mask:0xf bank_mask:0xf
	v_add_f32_dpp v49, v49, v49 quad_perm:[2,3,0,1] row_mask:0xf bank_mask:0xf
	v_add_f32_dpp v50, v50, v50 quad_perm:[2,3,0,1] row_mask:0xf bank_mask:0xf
	v_add_f32_dpp v51, v51, v51 quad_perm:[2,3,0,1] row_mask:0xf bank_mask:0xf
	v_add_f32_dpp v52, v52, v52 quad_perm:[2,3,0,1] row_mask:0xf bank_mask:0xf
	v_add_f32_dpp v53, v53, v53 quad_perm:[2,3,0,1] row_mask:0xf bank_mask:0xf
	v_add_f32_dpp v54, v54, v54 quad_perm:[2,3,0,1] row_mask:0xf bank_mask:0xf
	v_add_f32_dpp v55, v55, v55 quad_perm:[2,3,0,1] row_mask:0xf bank_mask:0xf
	v_add_f32_dpp v56, v56, v56 quad_perm:[2,3,0,1] row_mask:0xf bank_mask:0xf
	v_add_f32_dpp v57, v57, v57 quad_perm:[2,3,0,1] row_mask:0xf bank_mask:0xf
	v_add_f32_dpp v58, v58, v58 quad_perm:[2,3,0,1] row_mask:0xf bank_mask:0xf
	v_add_f32_dpp v59, v59, v59 quad_perm:[2,3,0,1] row_mask:0xf bank_mask:0xf
	v_add_f32_dpp v60, v60, v60 quad_perm:[2,3,0,1] row_mask:0xf bank_mask:0xf
	v_add_f32_dpp v61, v61, v61 quad_perm:[2,3,0,1] row_mask:0xf bank_mask:0xf
	v_add_f32_dpp v62, v62, v62 quad_perm:[2,3,0,1] row_mask:0xf bank_mask:0xf
	v_add_f32_dpp v63, v63, v63 quad_perm:[2,3,0,1] row_mask:0xf bank_mask:0xf
	v_add_f32_dpp v48, v48, v48 row_half_mirror row_mask:0xf bank_mask:0xf
	v_add_f32_dpp v49, v49, v49 row_half_mirror row_mask:0xf bank_mask:0xf
	v_add_f32_dpp v50, v50, v50 row_half_mirror row_mask:0xf bank_mask:0xf
	v_add_f32_dpp v51, v51, v51 row_half_mirror row_mask:0xf bank_mask:0xf
	v_add_f32_dpp v52, v52, v52 row_half_mirror row_mask:0xf bank_mask:0xf
	v_add_f32_dpp v53, v53, v53 row_half_mirror row_mask:0xf bank_mask:0xf
	v_add_f32_dpp v54, v54, v54 row_half_mirror row_mask:0xf bank_mask:0xf
	v_add_f32_dpp v55, v55, v55 row_half_mirror row_mask:0xf bank_mask:0xf
	v_add_f32_dpp v56, v56, v56 row_half_mirror row_mask:0xf bank_mask:0xf
	v_add_f32_dpp v57, v57, v57 row_half_mirror row_mask:0xf bank_mask:0xf
	v_add_f32_dpp v58, v58, v58 row_half_mirror row_mask:0xf bank_mask:0xf
	v_add_f32_dpp v59, v59, v59 row_half_mirror row_mask:0xf bank_mask:0xf
	v_add_f32_dpp v60, v60, v60 row_half_mirror row_mask:0xf bank_mask:0xf
	v_add_f32_dpp v61, v61, v61 row_half_mirror row_mask:0xf bank_mask:0xf
	v_add_f32_dpp v62, v62, v62 row_half_mirror row_mask:0xf bank_mask:0xf
	v_add_f32_dpp v63, v63, v63 row_half_mirror row_mask:0xf bank_mask:0xf
	v_add_f32_dpp v48, v48, v48 row_mirror row_mask:0xf bank_mask:0xf
	v_add_f32_dpp v49, v49, v49 row_mirror row_mask:0xf bank_mask:0xf
	v_add_f32_dpp v50, v50, v50 row_mirror row_mask:0xf bank_mask:0xf
	v_add_f32_dpp v51, v51, v51 row_mirror row_mask:0xf bank_mask:0xf
	v_add_f32_dpp v52, v52, v52 row_mirror row_mask:0xf bank_mask:0xf
	v_add_f32_dpp v53, v53, v53 row_mirror row_mask:0xf bank_mask:0xf
	v_add_f32_dpp v54, v54, v54 row_mirror row_mask:0xf bank_mask:0xf
	v_add_f32_dpp v55, v55, v55 row_mirror row_mask:0xf bank_mask:0xf
	v_add_f32_dpp v56, v56, v56 row_mirror row_mask:0xf bank_mask:0xf
	v_add_f32_dpp v57, v57, v57 row_mirror row_mask:0xf bank_mask:0xf
	v_add_f32_dpp v58, v58, v58 row_mirror row_mask:0xf bank_mask:0xf
	v_add_f32_dpp v59, v59, v59 row_mirror row_mask:0xf bank_mask:0xf
	v_add_f32_dpp v60, v60, v60 row_mirror row_mask:0xf bank_mask:0xf
	v_add_f32_dpp v61, v61, v61 row_mirror row_mask:0xf bank_mask:0xf
	v_add_f32_dpp v62, v62, v62 row_mirror row_mask:0xf bank_mask:0xf
	v_add_f32_dpp v63, v63, v63 row_mirror row_mask:0xf bank_mask:0xf
	v_mov_b32_e32 v64, v48
	v_mov_b32_e32 v65, v49
	v_mov_b32_e32 v66, v50
	v_mov_b32_e32 v67, v51
	v_mov_b32_e32 v68, v52
	v_mov_b32_e32 v69, v53
	v_mov_b32_e32 v70, v54
	v_mov_b32_e32 v71, v55
	v_mov_b32_e32 v72, v56
	v_mov_b32_e32 v73, v57
	v_mov_b32_e32 v74, v58
	v_mov_b32_e32 v75, v59
	v_mov_b32_e32 v76, v60
	v_mov_b32_e32 v77, v61
	v_mov_b32_e32 v78, v62
	v_mov_b32_e32 v79, v63
	v_permlane16_swap_b32_e32 v48, v64
	v_permlane16_swap_b32_e32 v49, v65
	v_permlane16_swap_b32_e32 v50, v66
	v_permlane16_swap_b32_e32 v51, v67
	v_permlane16_swap_b32_e32 v52, v68
	v_permlane16_swap_b32_e32 v53, v69
	v_permlane16_swap_b32_e32 v54, v70
	v_permlane16_swap_b32_e32 v55, v71
	v_permlane16_swap_b32_e32 v56, v72
	v_permlane16_swap_b32_e32 v57, v73
	v_permlane16_swap_b32_e32 v58, v74
	v_permlane16_swap_b32_e32 v59, v75
	v_permlane16_swap_b32_e32 v60, v76
	v_permlane16_swap_b32_e32 v61, v77
	v_permlane16_swap_b32_e32 v62, v78
	v_permlane16_swap_b32_e32 v63, v79
	v_add_f32_e32 v48, v48, v64
	v_add_f32_e32 v49, v49, v65
	v_add_f32_e32 v50, v50, v66
	v_add_f32_e32 v51, v51, v67
	v_add_f32_e32 v52, v52, v68
	v_add_f32_e32 v53, v53, v69
	v_add_f32_e32 v54, v54, v70
	v_add_f32_e32 v55, v55, v71
	v_add_f32_e32 v56, v56, v72
	v_add_f32_e32 v57, v57, v73
	v_add_f32_e32 v58, v58, v74
	v_add_f32_e32 v59, v59, v75
	v_add_f32_e32 v60, v60, v76
	v_add_f32_e32 v61, v61, v77
	v_add_f32_e32 v62, v62, v78
	v_add_f32_e32 v63, v63, v79
	v_mov_b32_e32 v64, v48
	v_mov_b32_e32 v65, v49
	v_mov_b32_e32 v66, v50
	v_mov_b32_e32 v67, v51
	v_mov_b32_e32 v68, v52
	v_mov_b32_e32 v69, v53
	v_mov_b32_e32 v70, v54
	v_mov_b32_e32 v71, v55
	v_mov_b32_e32 v72, v56
	v_mov_b32_e32 v73, v57
	v_mov_b32_e32 v74, v58
	v_mov_b32_e32 v75, v59
	v_mov_b32_e32 v76, v60
	v_mov_b32_e32 v77, v61
	v_mov_b32_e32 v78, v62
	v_mov_b32_e32 v79, v63
	v_permlane32_swap_b32_e32 v48, v64
	v_permlane32_swap_b32_e32 v49, v65
	v_permlane32_swap_b32_e32 v50, v66
	v_permlane32_swap_b32_e32 v51, v67
	v_permlane32_swap_b32_e32 v52, v68
	v_permlane32_swap_b32_e32 v53, v69
	v_permlane32_swap_b32_e32 v54, v70
	v_permlane32_swap_b32_e32 v55, v71
	v_permlane32_swap_b32_e32 v56, v72
	v_permlane32_swap_b32_e32 v57, v73
	v_permlane32_swap_b32_e32 v58, v74
	v_permlane32_swap_b32_e32 v59, v75
	v_permlane32_swap_b32_e32 v60, v76
	v_permlane32_swap_b32_e32 v61, v77
	v_permlane32_swap_b32_e32 v62, v78
	v_permlane32_swap_b32_e32 v63, v79
	v_add_f32_e32 v48, v48, v64
	v_add_f32_e32 v49, v49, v65
	v_add_f32_e32 v50, v50, v66
	v_add_f32_e32 v51, v51, v67
	v_add_f32_e32 v52, v52, v68
	v_add_f32_e32 v53, v53, v69
	v_add_f32_e32 v54, v54, v70
	v_add_f32_e32 v55, v55, v71
	v_add_f32_e32 v56, v56, v72
	v_add_f32_e32 v57, v57, v73
	v_add_f32_e32 v58, v58, v74
	v_add_f32_e32 v59, v59, v75
	v_add_f32_e32 v60, v60, v76
	v_add_f32_e32 v61, v61, v77
	v_add_f32_e32 v62, v62, v78
	v_add_f32_e32 v63, v63, v79
	v_fmamk_f32 v48, v48, 0x3c800000, v26
	v_fmamk_f32 v49, v49, 0x3c800000, v26
	v_fmamk_f32 v50, v50, 0x3c800000, v26
	v_fmamk_f32 v51, v51, 0x3c800000, v26
	v_fmamk_f32 v52, v52, 0x3c800000, v26
	v_fmamk_f32 v53, v53, 0x3c800000, v26
	v_fmamk_f32 v54, v54, 0x3c800000, v26
	v_fmamk_f32 v55, v55, 0x3c800000, v26
	v_fmamk_f32 v56, v56, 0x3d000000, v26
	v_fmamk_f32 v57, v57, 0x3d000000, v26
	v_fmamk_f32 v58, v58, 0x3d000000, v26
	v_fmamk_f32 v59, v59, 0x3d000000, v26
	v_fmamk_f32 v60, v60, 0x3d000000, v26
	v_fmamk_f32 v61, v61, 0x3d000000, v26
	v_fmamk_f32 v62, v62, 0x3d000000, v26
	v_fmamk_f32 v63, v63, 0x3d000000, v26
	v_rsq_f32_e32 v48, v48
	v_rsq_f32_e32 v49, v49
	v_rsq_f32_e32 v50, v50
	v_rsq_f32_e32 v51, v51
	v_rsq_f32_e32 v52, v52
	v_rsq_f32_e32 v53, v53
	v_rsq_f32_e32 v54, v54
	v_rsq_f32_e32 v55, v55
	v_rsq_f32_e32 v56, v56
	v_rsq_f32_e32 v57, v57
	v_rsq_f32_e32 v58, v58
	v_rsq_f32_e32 v59, v59
	v_rsq_f32_e32 v60, v60
	v_rsq_f32_e32 v61, v61
	v_rsq_f32_e32 v62, v62
	v_rsq_f32_e32 v63, v63
	s_nop 0
	v_mul_f32_e32 v30, v48, v30
	v_mul_f32_e32 v31, v49, v31
	v_mul_f32_e32 v32, v50, v32
	v_mul_f32_e32 v33, v51, v33
	v_mul_f32_e32 v34, v52, v34
	v_mul_f32_e32 v35, v53, v35
	v_mul_f32_e32 v36, v54, v36
	v_mul_f32_e32 v37, v55, v37
	v_mul_f32_e32 v30, v16, v30
	v_mul_f32_e32 v31, v16, v31
	v_mul_f32_e32 v32, v16, v32
	v_mul_f32_e32 v33, v16, v33
	v_mul_f32_e32 v34, v16, v34
	v_mul_f32_e32 v35, v16, v35
	v_mul_f32_e32 v36, v16, v36
	v_mul_f32_e32 v37, v16, v37
	v_mul_f32_e32 v30, 0x3dd105ec, v30
	v_mul_f32_e32 v31, 0x3dd105ec, v31
	v_mul_f32_e32 v32, 0x3dd105ec, v32
	v_mul_f32_e32 v33, 0x3dd105ec, v33
	v_mul_f32_e32 v34, 0x3dd105ec, v34
	v_mul_f32_e32 v35, 0x3dd105ec, v35
	v_mul_f32_e32 v36, 0x3dd105ec, v36
	v_mul_f32_e32 v37, 0x3dd105ec, v37
	v_cvt_pk_bf16_f32 v30, v30, s0
	v_cvt_pk_bf16_f32 v31, v31, s0
	v_cvt_pk_bf16_f32 v32, v32, s0
	v_cvt_pk_bf16_f32 v33, v33, s0
	v_cvt_pk_bf16_f32 v34, v34, s0
	v_cvt_pk_bf16_f32 v35, v35, s0
	v_cvt_pk_bf16_f32 v36, v36, s0
	v_cvt_pk_bf16_f32 v37, v37, s0
	global_store_short v[8:9], v30, off
	global_store_short v[8:9], v31, off offset:192
	global_store_short v[8:9], v32, off offset:384
	global_store_short v[8:9], v33, off offset:576
	global_store_short v[8:9], v34, off offset:768
	global_store_short v[8:9], v35, off offset:960
	global_store_short v[8:9], v36, off offset:1152
	global_store_short v[8:9], v37, off offset:1344
	v_mul_f32_e32 v38, v38, v56
	v_mul_f32_e32 v39, v39, v57
	v_mul_f32_e32 v40, v40, v58
	v_mul_f32_e32 v41, v41, v59
	v_mul_f32_e32 v42, v42, v60
	v_mul_f32_e32 v43, v43, v61
	v_mul_f32_e32 v44, v44, v62
	v_mul_f32_e32 v45, v45, v63
	v_mul_f32_e32 v38, v17, v38
	v_mul_f32_e32 v39, v17, v39
	v_mul_f32_e32 v40, v17, v40
	v_mul_f32_e32 v41, v17, v41
	v_mul_f32_e32 v42, v17, v42
	v_mul_f32_e32 v43, v17, v43
	v_mul_f32_e32 v44, v17, v44
	v_mul_f32_e32 v45, v17, v45
	ds_bpermute_b32 v64, v19, v38
	ds_bpermute_b32 v65, v19, v39
	ds_bpermute_b32 v66, v19, v40
	ds_bpermute_b32 v67, v19, v41
	ds_bpermute_b32 v68, v19, v42
	ds_bpermute_b32 v69, v19, v43
	ds_bpermute_b32 v70, v19, v44
	ds_bpermute_b32 v71, v19, v45
	s_waitcnt lgkmcnt(0)
	v_mul_f32_e32 v64, v47, v64
	v_mul_f32_e32 v65, v47, v65
	v_mul_f32_e32 v66, v47, v66
	v_mul_f32_e32 v67, v47, v67
	v_mul_f32_e32 v68, v47, v68
	v_mul_f32_e32 v69, v47, v69
	v_mul_f32_e32 v70, v47, v70
	v_mul_f32_e32 v71, v47, v71
	v_cndmask_b32_e64 v64, v64, -v64, s[0:1]
	v_cndmask_b32_e64 v65, v65, -v65, s[0:1]
	v_cndmask_b32_e64 v66, v66, -v66, s[0:1]
	v_cndmask_b32_e64 v67, v67, -v67, s[0:1]
	v_cndmask_b32_e64 v68, v68, -v68, s[0:1]
	v_cndmask_b32_e64 v69, v69, -v69, s[0:1]
	v_cndmask_b32_e64 v70, v70, -v70, s[0:1]
	v_cndmask_b32_e64 v71, v71, -v71, s[0:1]
	v_fmac_f32_e32 v64, v38, v46
	v_fmac_f32_e32 v65, v39, v46
	v_fmac_f32_e32 v66, v40, v46
	v_fmac_f32_e32 v67, v41, v46
	v_fmac_f32_e32 v68, v42, v46
	v_fmac_f32_e32 v69, v43, v46
	v_fmac_f32_e32 v70, v44, v46
	v_fmac_f32_e32 v71, v45, v46
	v_mul_f32_e32 v64, 0x3dd105ec, v64
	v_mul_f32_e32 v65, 0x3dd105ec, v65
	v_mul_f32_e32 v66, 0x3dd105ec, v66
	v_mul_f32_e32 v67, 0x3dd105ec, v67
	v_mul_f32_e32 v68, 0x3dd105ec, v68
	v_mul_f32_e32 v69, 0x3dd105ec, v69
	v_mul_f32_e32 v70, 0x3dd105ec, v70
	v_mul_f32_e32 v71, 0x3dd105ec, v71
	v_cvt_pk_bf16_f32 v64, v64, s0
	v_cvt_pk_bf16_f32 v65, v65, s0
	v_cvt_pk_bf16_f32 v66, v66, s0
	v_cvt_pk_bf16_f32 v67, v67, s0
	v_cvt_pk_bf16_f32 v68, v68, s0
	v_cvt_pk_bf16_f32 v69, v69, s0
	v_cvt_pk_bf16_f32 v70, v70, s0
	v_cvt_pk_bf16_f32 v71, v71, s0
	s_and_saveexec_b64 s[8:9], vcc
	global_store_short v[8:9], v64, off offset:128
	global_store_short v[8:9], v65, off offset:320
	global_store_short v[8:9], v66, off offset:512
	global_store_short v[8:9], v67, off offset:704
	global_store_short v[8:9], v68, off offset:896
	global_store_short v[8:9], v69, off offset:1088
	global_store_short v[8:9], v70, off offset:1280
	global_store_short v[8:9], v71, off offset:1472
	s_or_b64 exec, exec, s[8:9]
	s_branch .LBB0_708
